# differential-attention KV-loop body rewritten by hand: batched K/V fragment reads, far-tile bias folded into the max offset, batched distance-bias lookups for near tiles, packed sub/sum
# speedup vs baseline: 1.0239x; 1.0200x over previous
; #define LAS __attribute__((address_space(3)))
; __device__ __forceinline__ f32x16 mma32(const h16x8 a, const h16x8 b, const f32x16 c) { return __builtin_amdgcn_mfma_f32_32x32x16_f16(a, b, c, 0, 0, 0); }
; __device__ __forceinline__ void diff_attn_item(CParams& p, int j, int layer, LAS unsigned char* lds, int b, int h, int qb, int tid_in, int lane_in, int wave) {
;     ...
;     for (int kt = 0; kt < nkt; ++kt) {
;         const int k0 = kt * 64; const int cur = kt & 1;
;         const LAS h16* Ks = Ks0 + cur * 8704; const LAS h16* Vt = Vt0 + cur * 9216;
;         if (kt + 1 < nkt) ATT_STAGE(cur ^ 1, 512 + h * 128, 1024 + h * 128, kt + 2);
;         if (!(k0 > q0 + 31)) {
;         f32x16 sc[2];
; #pragma unroll
;         for (int sub = 0; sub < 2; ++sub) {
; #pragma unroll
;             for (int i = 0; i < 16; ++i) sc[sub][i] = 0.f;
; #pragma unroll
;             for (int s = 0; s < 4; ++s) sc[sub] = mma32(*(const LAS h16x8*)(Ks + (32 * sub + r) * 136 + mp * 64 + 16 * s + 8 * hh), qf[s], sc[sub]);
;         }
;         float mx = -INFINITY;
;         if (k0 + 63 + 128 <= q0) {
;             const float bfar = bdl[128];
; #pragma unroll
;             for (int sub = 0; sub < 2; ++sub)
; #pragma unroll
;                 for (int i = 0; i < 16; ++i) { sc[sub][i] += bfar; mx = fmaxf(mx, sc[sub][i]); }
;         } else {
; #pragma unroll
;             for (int sub = 0; sub < 2; ++sub)
; #pragma unroll
;                 for (int i = 0; i < 16; ++i) { const int kp = k0 + 32 * sub + (i & 3) + 8 * (i >> 2) + 4 * hh; const int dist = qp - kp;
;                     const float v = dist < 0 ? -INFINITY : sc[sub][i] + bdl[dist < 128 ? dist : 128]; sc[sub][i] = v; mx = fmaxf(mx, v); }
;         }
.LBB0_598:
	s_and_b32 s41, s38, 1
	s_xor_b32 s4, s41, 1
	s_mul_i32 s5, s4, 0x4400
	s_mulk_i32 s4, 0x4800
	s_add_i32 s6, s40, 0xffffff41
	v_add_u32_e32 v66, s4, v205
	s_add_i32 s4, s38, 2
	s_cmp_lt_u32 s38, s37
	v_add3_u32 v67, v202, s5, v203
	v_add3_u32 v68, v66, v206, v204
	s_cselect_b32 s4, s4, s39
	s_waitcnt vmcnt(3)
	ds_write_b128 v67, v[126:129]
	s_waitcnt vmcnt(2)
	ds_write_b16 v68, v118 offset:34816
	ds_write_b16_d16_hi v68, v118 offset:34960
	ds_write_b16 v68, v119 offset:35104
	ds_write_b16_d16_hi v68, v119 offset:35248
	ds_write_b16 v68, v120 offset:35392
	ds_write_b16_d16_hi v68, v120 offset:35536
	ds_write_b16 v68, v121 offset:35680
	ds_write_b16_d16_hi v68, v121 offset:35824
	s_waitcnt vmcnt(1)
	ds_write_b128 v67, v[122:125] offset:8704
	v_add3_u32 v66, v66, v207, v204
	v_lshl_add_u32 v68, s4, 6, v200
	s_waitcnt vmcnt(0)
	ds_write_b16 v66, v114 offset:34816
	ds_write_b16_d16_hi v66, v114 offset:34960
	ds_write_b16 v66, v115 offset:35104
	ds_write_b16_d16_hi v66, v115 offset:35248
	ds_write_b16 v66, v116 offset:35392
	ds_write_b16_d16_hi v66, v116 offset:35536
	ds_write_b16 v66, v117 offset:35680
	ds_write_b16_d16_hi v66, v117 offset:35824
	v_mad_i64_i32 v[66:67], s[4:5], v68, s33, v[130:131]
	global_load_dwordx4 v[126:129], v[66:67], off offset:1024
	global_load_dwordx4 v[118:121], v[66:67], off offset:2048
	v_add_u32_e32 v66, 32, v68
	v_mad_i64_i32 v[66:67], s[4:5], v66, s33, v[130:131]
	global_load_dwordx4 v[122:125], v[66:67], off offset:1024
	global_load_dwordx4 v[114:117], v[66:67], off offset:2048
	v_cmp_le_u32_e32 vcc, s6, v210
	s_and_saveexec_b64 s[4:5], vcc
	s_cbranch_execz .LBB0_670
	s_mul_i32 s6, s41, 0x4400
	v_add_u32_e32 v214, s6, v211
	ds_read_b128 v[66:69], v214 offset:0
	ds_read_b128 v[70:73], v214 offset:32
	ds_read_b128 v[74:77], v214 offset:64
	ds_read_b128 v[78:81], v214 offset:96
	ds_read_b128 v[82:85], v214 offset:8704
	ds_read_b128 v[86:89], v214 offset:8736
	ds_read_b128 v[90:93], v214 offset:8768
	ds_read_b128 v[94:97], v214 offset:8800
	s_mulk_i32 s41, 0x4800
	v_add_u32_e32 v215, s41, v195
	v_lshl_add_u32 v227, v194, 1, v215
	v_add_u32_e32 v215, v215, v196
	v_readfirstlane_b32 s6, v199
	s_mov_b32 s7, 0x11800
	s_waitcnt lgkmcnt(4)
	v_mfma_f32_32x32x16_f16 v[162:177], v[66:69], v[110:113], 0
	v_mfma_f32_32x32x16_f16 v[162:177], v[70:73], v[106:109], v[162:177]
	v_mfma_f32_32x32x16_f16 v[162:177], v[74:77], v[102:105], v[162:177]
	v_mfma_f32_32x32x16_f16 v[162:177], v[78:81], v[98:101], v[162:177]
	s_waitcnt lgkmcnt(0)
	v_mfma_f32_32x32x16_f16 v[228:243], v[82:85], v[110:113], 0
	v_mfma_f32_32x32x16_f16 v[228:243], v[86:89], v[106:109], v[228:243]
	v_mfma_f32_32x32x16_f16 v[228:243], v[90:93], v[102:105], v[228:243]
	v_mfma_f32_32x32x16_f16 v[228:243], v[94:97], v[98:101], v[228:243]
	s_sub_u32 s6, s6, s40
	s_add_u32 s6, s6, 0xbf
	s_cmp_ge_i32 s6, 0xbf
	s_cbranch_scc1 .LdiffA_far
	s_andn2_b32 s12, s6, 32
	s_cmp_eq_u32 s12, 64
	s_cbranch_scc1 .LdiffA_mid
	s_movk_i32 s12, 0x80
	v_add_u32_e32 v66, 59, v212
	v_med3_i32 v66, v66, 0, s12
	v_lshl_add_u32 v66, v66, 2, s7
	ds_read_b32 v66, v66
	v_add_u32_e32 v67, 58, v212
	v_med3_i32 v67, v67, 0, s12
	v_lshl_add_u32 v67, v67, 2, s7
	ds_read_b32 v67, v67
	v_add_u32_e32 v68, 57, v212
	v_med3_i32 v68, v68, 0, s12
	v_lshl_add_u32 v68, v68, 2, s7
	ds_read_b32 v68, v68
	v_add_u32_e32 v69, 56, v212
	v_med3_i32 v69, v69, 0, s12
	v_lshl_add_u32 v69, v69, 2, s7
	ds_read_b32 v69, v69
	v_add_u32_e32 v70, 51, v212
	v_med3_i32 v70, v70, 0, s12
	v_lshl_add_u32 v70, v70, 2, s7
	ds_read_b32 v70, v70
	v_add_u32_e32 v71, 50, v212
	v_med3_i32 v71, v71, 0, s12
	v_lshl_add_u32 v71, v71, 2, s7
	ds_read_b32 v71, v71
	v_add_u32_e32 v72, 49, v212
	v_med3_i32 v72, v72, 0, s12
	v_lshl_add_u32 v72, v72, 2, s7
	ds_read_b32 v72, v72
	v_add_u32_e32 v73, 48, v212
	v_med3_i32 v73, v73, 0, s12
	v_lshl_add_u32 v73, v73, 2, s7
	ds_read_b32 v73, v73
	v_add_u32_e32 v74, 43, v212
	v_med3_i32 v74, v74, 0, s12
	v_lshl_add_u32 v74, v74, 2, s7
	ds_read_b32 v74, v74
	v_add_u32_e32 v75, 42, v212
	v_med3_i32 v75, v75, 0, s12
	v_lshl_add_u32 v75, v75, 2, s7
	ds_read_b32 v75, v75
	v_add_u32_e32 v76, 41, v212
	v_med3_i32 v76, v76, 0, s12
	v_lshl_add_u32 v76, v76, 2, s7
	ds_read_b32 v76, v76
	v_add_u32_e32 v77, 40, v212
	v_med3_i32 v77, v77, 0, s12
	v_lshl_add_u32 v77, v77, 2, s7
	ds_read_b32 v77, v77
	v_add_u32_e32 v78, 35, v212
	v_med3_i32 v78, v78, 0, s12
	v_lshl_add_u32 v78, v78, 2, s7
	ds_read_b32 v78, v78
	v_add_u32_e32 v79, 34, v212
	v_med3_i32 v79, v79, 0, s12
	v_lshl_add_u32 v79, v79, 2, s7
	ds_read_b32 v79, v79
	v_add_u32_e32 v80, 33, v212
	v_med3_i32 v80, v80, 0, s12
	v_lshl_add_u32 v80, v80, 2, s7
	ds_read_b32 v80, v80
	v_add_u32_e32 v81, 32, v212
	v_med3_i32 v81, v81, 0, s12
	v_lshl_add_u32 v81, v81, 2, s7
	ds_read_b32 v81, v81
	v_add_u32_e32 v82, 27, v212
	v_med3_i32 v82, v82, 0, s12
	v_lshl_add_u32 v82, v82, 2, s7
	ds_read_b32 v82, v82
	v_add_u32_e32 v83, 26, v212
	v_med3_i32 v83, v83, 0, s12
	v_lshl_add_u32 v83, v83, 2, s7
	ds_read_b32 v83, v83
	v_add_u32_e32 v84, 25, v212
	v_med3_i32 v84, v84, 0, s12
	v_lshl_add_u32 v84, v84, 2, s7
	ds_read_b32 v84, v84
	v_add_u32_e32 v85, 24, v212
	v_med3_i32 v85, v85, 0, s12
	v_lshl_add_u32 v85, v85, 2, s7
	ds_read_b32 v85, v85
	v_add_u32_e32 v86, 19, v212
	v_med3_i32 v86, v86, 0, s12
	v_lshl_add_u32 v86, v86, 2, s7
	ds_read_b32 v86, v86
	v_add_u32_e32 v87, 18, v212
	v_med3_i32 v87, v87, 0, s12
	v_lshl_add_u32 v87, v87, 2, s7
	ds_read_b32 v87, v87
	v_add_u32_e32 v88, 17, v212
	v_med3_i32 v88, v88, 0, s12
	v_lshl_add_u32 v88, v88, 2, s7
	ds_read_b32 v88, v88
	v_add_u32_e32 v89, 16, v212
	v_med3_i32 v89, v89, 0, s12
	v_lshl_add_u32 v89, v89, 2, s7
	ds_read_b32 v89, v89
	v_add_u32_e32 v90, 11, v212
	v_med3_i32 v90, v90, 0, s12
	v_lshl_add_u32 v90, v90, 2, s7
	ds_read_b32 v90, v90
	v_add_u32_e32 v91, 10, v212
	v_med3_i32 v91, v91, 0, s12
	v_lshl_add_u32 v91, v91, 2, s7
	ds_read_b32 v91, v91
	v_add_u32_e32 v92, 9, v212
	v_med3_i32 v92, v92, 0, s12
	v_lshl_add_u32 v92, v92, 2, s7
	ds_read_b32 v92, v92
	v_add_u32_e32 v93, 8, v212
	v_med3_i32 v93, v93, 0, s12
	v_lshl_add_u32 v93, v93, 2, s7
	ds_read_b32 v93, v93
	v_add_u32_e32 v94, 3, v212
	v_med3_i32 v94, v94, 0, s12
	v_lshl_add_u32 v94, v94, 2, s7
	ds_read_b32 v94, v94
	v_add_u32_e32 v95, 2, v212
	v_med3_i32 v95, v95, 0, s12
	v_lshl_add_u32 v95, v95, 2, s7
	ds_read_b32 v95, v95
	v_add_u32_e32 v96, 1, v212
	v_med3_i32 v96, v96, 0, s12
	v_lshl_add_u32 v96, v96, 2, s7
	ds_read_b32 v96, v96
	v_add_u32_e32 v97, 0, v212
	v_med3_i32 v97, v97, 0, s12
	v_lshl_add_u32 v97, v97, 2, s7
	ds_read_b32 v97, v97
	v_sub_u32_e32 v145, 0, v212
	v_mov_b32_e32 v144, 0xff800000
	s_nop 4
	s_waitcnt lgkmcnt(0)
; __device__ __forceinline__ void diff_attn_item(CParams& p, int j, int layer, LAS unsigned char* lds, int b, int h, int qb, int tid_in, int lane_in, int wave) {
;     ...
; #pragma unroll
;             for (int sub = 0; sub < 2; ++sub)
; #pragma unroll
;                 for (int i = 0; i < 16; ++i) { const int kp = k0 + 32 * sub + (i & 3) + 8 * (i >> 2) + 4 * hh; const int dist = qp - kp;
;                     const float v = dist < 0 ? -INFINITY : sc[sub][i] + bdl[dist < 128 ? dist : 128]; sc[sub][i] = v; mx = fmaxf(mx, v); }
;         }
	v_pk_add_f32 v[162:163], v[162:163], v[66:67]
	v_pk_add_f32 v[164:165], v[164:165], v[68:69]
	v_pk_add_f32 v[166:167], v[166:167], v[70:71]
	v_pk_add_f32 v[168:169], v[168:169], v[72:73]
	v_pk_add_f32 v[170:171], v[170:171], v[74:75]
	v_pk_add_f32 v[172:173], v[172:173], v[76:77]
	v_pk_add_f32 v[174:175], v[174:175], v[78:79]
	v_pk_add_f32 v[176:177], v[176:177], v[80:81]
	v_pk_add_f32 v[228:229], v[228:229], v[82:83]
	v_pk_add_f32 v[230:231], v[230:231], v[84:85]
	v_pk_add_f32 v[232:233], v[232:233], v[86:87]
	v_pk_add_f32 v[234:235], v[234:235], v[88:89]
	v_pk_add_f32 v[236:237], v[236:237], v[90:91]
	v_pk_add_f32 v[238:239], v[238:239], v[92:93]
	v_pk_add_f32 v[240:241], v[240:241], v[94:95]
	v_pk_add_f32 v[242:243], v[242:243], v[96:97]
	v_cmp_ge_i32_e64 s[46:47], 59, v145
	v_cmp_ge_i32_e64 s[48:49], 58, v145
	v_cmp_ge_i32_e64 s[50:51], 57, v145
	v_cndmask_b32_e64 v162, v144, v162, s[46:47]
	v_cmp_ge_i32_e64 s[52:53], 56, v145
	v_cndmask_b32_e64 v163, v144, v163, s[48:49]
	v_cmp_ge_i32_e64 s[46:47], 51, v145
	v_cndmask_b32_e64 v164, v144, v164, s[50:51]
	v_cmp_ge_i32_e64 s[48:49], 50, v145
	v_cndmask_b32_e64 v165, v144, v165, s[52:53]
	v_cmp_ge_i32_e64 s[50:51], 49, v145
	v_cndmask_b32_e64 v166, v144, v166, s[46:47]
	v_cmp_ge_i32_e64 s[52:53], 48, v145
	v_cndmask_b32_e64 v167, v144, v167, s[48:49]
	v_cmp_ge_i32_e64 s[46:47], 43, v145
	v_cndmask_b32_e64 v168, v144, v168, s[50:51]
	v_cmp_ge_i32_e64 s[48:49], 42, v145
	v_cndmask_b32_e64 v169, v144, v169, s[52:53]
	v_cmp_ge_i32_e64 s[50:51], 41, v145
	v_cndmask_b32_e64 v170, v144, v170, s[46:47]
	v_cmp_ge_i32_e64 s[52:53], 40, v145
	v_cndmask_b32_e64 v171, v144, v171, s[48:49]
	v_cmp_ge_i32_e64 s[46:47], 35, v145
	v_cndmask_b32_e64 v172, v144, v172, s[50:51]
	v_cmp_ge_i32_e64 s[48:49], 34, v145
	v_cndmask_b32_e64 v173, v144, v173, s[52:53]
	v_cmp_ge_i32_e64 s[50:51], 33, v145
	v_cndmask_b32_e64 v174, v144, v174, s[46:47]
	v_cmp_ge_i32_e64 s[52:53], 32, v145
	v_cndmask_b32_e64 v175, v144, v175, s[48:49]
	v_cmp_ge_i32_e64 s[46:47], 27, v145
	v_cndmask_b32_e64 v176, v144, v176, s[50:51]
	v_cmp_ge_i32_e64 s[48:49], 26, v145
	v_cndmask_b32_e64 v177, v144, v177, s[52:53]
	v_cmp_ge_i32_e64 s[50:51], 25, v145
	v_cndmask_b32_e64 v228, v144, v228, s[46:47]
	v_cmp_ge_i32_e64 s[52:53], 24, v145
	v_cndmask_b32_e64 v229, v144, v229, s[48:49]
	v_cmp_ge_i32_e64 s[46:47], 19, v145
	v_cndmask_b32_e64 v230, v144, v230, s[50:51]
	v_cmp_ge_i32_e64 s[48:49], 18, v145
	v_cndmask_b32_e64 v231, v144, v231, s[52:53]
	v_cmp_ge_i32_e64 s[50:51], 17, v145
	v_cndmask_b32_e64 v232, v144, v232, s[46:47]
	v_cmp_ge_i32_e64 s[52:53], 16, v145
	v_cndmask_b32_e64 v233, v144, v233, s[48:49]
	v_cmp_ge_i32_e64 s[46:47], 11, v145
	v_cndmask_b32_e64 v234, v144, v234, s[50:51]
	v_cmp_ge_i32_e64 s[48:49], 10, v145
	v_cndmask_b32_e64 v235, v144, v235, s[52:53]
	v_cmp_ge_i32_e64 s[50:51], 9, v145
	v_cndmask_b32_e64 v236, v144, v236, s[46:47]
	v_cmp_ge_i32_e64 s[52:53], 8, v145
	v_cndmask_b32_e64 v237, v144, v237, s[48:49]
	v_cmp_ge_i32_e64 s[46:47], 3, v145
	v_cndmask_b32_e64 v238, v144, v238, s[50:51]
	v_cmp_ge_i32_e64 s[48:49], 2, v145
	v_cndmask_b32_e64 v239, v144, v239, s[52:53]
	v_cmp_ge_i32_e64 s[50:51], 1, v145
	v_cndmask_b32_e64 v240, v144, v240, s[46:47]
	v_cmp_ge_i32_e64 s[52:53], 0, v145
	v_cndmask_b32_e64 v241, v144, v241, s[48:49]
	v_cndmask_b32_e64 v242, v144, v242, s[50:51]
	v_cndmask_b32_e64 v243, v144, v243, s[52:53]
	v_mov_b32_e32 v213, 0
	s_branch .LdiffA_max
.LdiffA_mid:
	v_lshl_add_u32 v214, v212, 2, s7
	ds_read_b32 v66, v214 offset:236
	ds_read_b32 v67, v214 offset:232
	ds_read_b32 v68, v214 offset:228
	ds_read_b32 v69, v214 offset:224
	ds_read_b32 v70, v214 offset:204
	ds_read_b32 v71, v214 offset:200
	ds_read_b32 v72, v214 offset:196
	ds_read_b32 v73, v214 offset:192
	ds_read_b32 v74, v214 offset:172
	ds_read_b32 v75, v214 offset:168
	ds_read_b32 v76, v214 offset:164
	ds_read_b32 v77, v214 offset:160
	ds_read_b32 v78, v214 offset:140
	ds_read_b32 v79, v214 offset:136
	ds_read_b32 v80, v214 offset:132
	ds_read_b32 v81, v214 offset:128
	ds_read_b32 v82, v214 offset:108
	ds_read_b32 v83, v214 offset:104
	ds_read_b32 v84, v214 offset:100
	ds_read_b32 v85, v214 offset:96
	ds_read_b32 v86, v214 offset:76
	ds_read_b32 v87, v214 offset:72
	ds_read_b32 v88, v214 offset:68
	ds_read_b32 v89, v214 offset:64
	ds_read_b32 v90, v214 offset:44
	ds_read_b32 v91, v214 offset:40
	ds_read_b32 v92, v214 offset:36
	ds_read_b32 v93, v214 offset:32
	ds_read_b32 v94, v214 offset:12
	ds_read_b32 v95, v214 offset:8
	ds_read_b32 v96, v214 offset:4
	ds_read_b32 v97, v214 offset:0
	v_mov_b32_e32 v213, 0
	s_nop 4
	s_waitcnt lgkmcnt(0)
	v_pk_add_f32 v[162:163], v[162:163], v[66:67]
	v_pk_add_f32 v[164:165], v[164:165], v[68:69]
	v_pk_add_f32 v[166:167], v[166:167], v[70:71]
	v_pk_add_f32 v[168:169], v[168:169], v[72:73]
	v_pk_add_f32 v[170:171], v[170:171], v[74:75]
	v_pk_add_f32 v[172:173], v[172:173], v[76:77]
	v_pk_add_f32 v[174:175], v[174:175], v[78:79]
	v_pk_add_f32 v[176:177], v[176:177], v[80:81]
	v_pk_add_f32 v[228:229], v[228:229], v[82:83]
	v_pk_add_f32 v[230:231], v[230:231], v[84:85]
	v_pk_add_f32 v[232:233], v[232:233], v[86:87]
	v_pk_add_f32 v[234:235], v[234:235], v[88:89]
	v_pk_add_f32 v[236:237], v[236:237], v[90:91]
	v_pk_add_f32 v[238:239], v[238:239], v[92:93]
	v_pk_add_f32 v[240:241], v[240:241], v[94:95]
	v_pk_add_f32 v[242:243], v[242:243], v[96:97]
	s_branch .LdiffA_max
.LdiffA_far:
	v_mov_b32_e32 v214, 0x11a00
	ds_read_b32 v213, v214
	s_nop 6
; __device__ __forceinline__ void diff_attn_item(CParams& p, int j, int layer, LAS unsigned char* lds, int b, int h, int qb, int tid_in, int lane_in, int wave) {
;     ...
;         mx = fmaxf(mx, __shfl_xor(mx, 32));
;         const float m_new = fmaxf(m_run, mx);
;         const float alpha = __builtin_amdgcn_exp2f(m_run - m_new);
;         const bool resc = __ballot(m_new > m_run) != 0ull;
;         float ls = 0.f;
; #pragma unroll
;         for (int sub = 0; sub < 2; ++sub)
; #pragma unroll
;             for (int i = 0; i < 16; ++i) { const float e = __builtin_amdgcn_exp2f(sc[sub][i] - m_new); sc[sub][i] = e; ls += e; }
;         ls += __shfl_xor(ls, 32);
;         l_run = l_run * alpha + ls; m_run = m_new;
;         if (resc) {
; #pragma unroll
;             for (int d = 0; d < 4; ++d)
; #pragma unroll
;                 for (int i = 0; i < 16; ++i) o[d][i] *= alpha;
;         }
.LdiffA_max:
	v_max3_f32 v249, v162, v163, v164
	v_max3_f32 v249, v249, v165, v166
	v_max3_f32 v249, v249, v167, v168
	v_max3_f32 v249, v249, v169, v170
	v_max3_f32 v249, v249, v171, v172
	v_max3_f32 v249, v249, v173, v174
	v_max3_f32 v249, v249, v175, v176
	v_max3_f32 v249, v249, v177, v228
	v_max3_f32 v249, v249, v229, v230
	v_max3_f32 v249, v249, v231, v232
	v_max3_f32 v249, v249, v233, v234
	v_max3_f32 v249, v249, v235, v236
	v_max3_f32 v249, v249, v237, v238
	v_max3_f32 v249, v249, v239, v240
	v_max3_f32 v249, v249, v241, v242
	v_max_f32_e32 v249, v249, v243
	s_waitcnt lgkmcnt(0)
	v_add_f32_e32 v249, v249, v213
	ds_bpermute_b32 v251, v185, v249
	s_waitcnt lgkmcnt(0)
	v_max3_f32 v248, v201, v249, v251
	v_sub_f32_e32 v244, v201, v248
	v_exp_f32_e32 v244, v244
	v_cmp_gt_f32_e32 vcc, v248, v201
	v_sub_f32_e32 v246, v248, v213
	v_mov_b32_e32 v201, v248
	v_pk_add_f32 v[162:163], v[162:163], v[246:247] op_sel_hi:[1,0] neg_lo:[0,1] neg_hi:[0,1]
	v_pk_add_f32 v[164:165], v[164:165], v[246:247] op_sel_hi:[1,0] neg_lo:[0,1] neg_hi:[0,1]
	v_pk_add_f32 v[166:167], v[166:167], v[246:247] op_sel_hi:[1,0] neg_lo:[0,1] neg_hi:[0,1]
	v_pk_add_f32 v[168:169], v[168:169], v[246:247] op_sel_hi:[1,0] neg_lo:[0,1] neg_hi:[0,1]
	v_pk_add_f32 v[170:171], v[170:171], v[246:247] op_sel_hi:[1,0] neg_lo:[0,1] neg_hi:[0,1]
	v_pk_add_f32 v[172:173], v[172:173], v[246:247] op_sel_hi:[1,0] neg_lo:[0,1] neg_hi:[0,1]
	v_pk_add_f32 v[174:175], v[174:175], v[246:247] op_sel_hi:[1,0] neg_lo:[0,1] neg_hi:[0,1]
	v_pk_add_f32 v[176:177], v[176:177], v[246:247] op_sel_hi:[1,0] neg_lo:[0,1] neg_hi:[0,1]
	v_pk_add_f32 v[228:229], v[228:229], v[246:247] op_sel_hi:[1,0] neg_lo:[0,1] neg_hi:[0,1]
	v_pk_add_f32 v[230:231], v[230:231], v[246:247] op_sel_hi:[1,0] neg_lo:[0,1] neg_hi:[0,1]
	v_pk_add_f32 v[232:233], v[232:233], v[246:247] op_sel_hi:[1,0] neg_lo:[0,1] neg_hi:[0,1]
	v_pk_add_f32 v[234:235], v[234:235], v[246:247] op_sel_hi:[1,0] neg_lo:[0,1] neg_hi:[0,1]
	v_pk_add_f32 v[236:237], v[236:237], v[246:247] op_sel_hi:[1,0] neg_lo:[0,1] neg_hi:[0,1]
	v_pk_add_f32 v[238:239], v[238:239], v[246:247] op_sel_hi:[1,0] neg_lo:[0,1] neg_hi:[0,1]
	v_pk_add_f32 v[240:241], v[240:241], v[246:247] op_sel_hi:[1,0] neg_lo:[0,1] neg_hi:[0,1]
	v_pk_add_f32 v[242:243], v[242:243], v[246:247] op_sel_hi:[1,0] neg_lo:[0,1] neg_hi:[0,1]
	v_exp_f32_e32 v162, v162
	v_exp_f32_e32 v163, v163
	v_exp_f32_e32 v164, v164
	v_exp_f32_e32 v165, v165
	v_exp_f32_e32 v166, v166
	v_exp_f32_e32 v167, v167
	v_exp_f32_e32 v168, v168
	v_exp_f32_e32 v169, v169
	v_exp_f32_e32 v170, v170
	v_exp_f32_e32 v171, v171
	v_exp_f32_e32 v172, v172
	v_exp_f32_e32 v173, v173
	v_exp_f32_e32 v174, v174
	v_exp_f32_e32 v175, v175
	v_exp_f32_e32 v176, v176
	v_exp_f32_e32 v177, v177
	v_exp_f32_e32 v228, v228
	v_exp_f32_e32 v229, v229
	v_exp_f32_e32 v230, v230
	v_exp_f32_e32 v231, v231
	v_exp_f32_e32 v232, v232
	v_exp_f32_e32 v233, v233
	v_exp_f32_e32 v234, v234
	v_exp_f32_e32 v235, v235
	v_exp_f32_e32 v236, v236
	v_exp_f32_e32 v237, v237
	v_exp_f32_e32 v238, v238
	v_exp_f32_e32 v239, v239
	v_exp_f32_e32 v240, v240
	v_exp_f32_e32 v241, v241
	v_exp_f32_e32 v242, v242
	v_exp_f32_e32 v243, v243
	v_pk_add_f32 v[250:251], v[162:163], v[164:165]
	v_pk_add_f32 v[250:251], v[250:251], v[166:167]
	v_pk_add_f32 v[250:251], v[250:251], v[168:169]
	v_pk_add_f32 v[250:251], v[250:251], v[170:171]
	v_pk_add_f32 v[250:251], v[250:251], v[172:173]
	v_pk_add_f32 v[250:251], v[250:251], v[174:175]
	v_pk_add_f32 v[250:251], v[250:251], v[176:177]
	v_pk_add_f32 v[250:251], v[250:251], v[228:229]
	v_pk_add_f32 v[250:251], v[250:251], v[230:231]
	v_pk_add_f32 v[250:251], v[250:251], v[232:233]
	v_pk_add_f32 v[250:251], v[250:251], v[234:235]
	v_pk_add_f32 v[250:251], v[250:251], v[236:237]
	v_pk_add_f32 v[250:251], v[250:251], v[238:239]
	v_pk_add_f32 v[250:251], v[250:251], v[240:241]
	v_pk_add_f32 v[250:251], v[250:251], v[242:243]
	s_nop 0
	v_add_f32_e32 v250, v250, v251
	ds_bpermute_b32 v251, v185, v250
	v_cvt_pk_f16_f32 v144, v162, v163
	v_cvt_pk_f16_f32 v145, v164, v165
	v_cvt_pk_f16_f32 v146, v166, v167
	v_cvt_pk_f16_f32 v147, v168, v169
	v_cvt_pk_f16_f32 v148, v170, v171
	v_cvt_pk_f16_f32 v149, v172, v173
	v_cvt_pk_f16_f32 v150, v174, v175
	v_cvt_pk_f16_f32 v151, v176, v177
	v_cvt_pk_f16_f32 v152, v228, v229
	v_cvt_pk_f16_f32 v153, v230, v231
	v_cvt_pk_f16_f32 v154, v232, v233
	v_cvt_pk_f16_f32 v155, v234, v235
	v_cvt_pk_f16_f32 v178, v236, v237
	v_cvt_pk_f16_f32 v179, v238, v239
	v_cvt_pk_f16_f32 v180, v240, v241
	v_cvt_pk_f16_f32 v181, v242, v243
	s_waitcnt lgkmcnt(0)
	v_add_f32_e32 v250, v250, v251
	v_fma_f32 v197, v197, v244, v250
	ds_read_b64 v[66:67], v215 offset:34816
	ds_read_b64 v[68:69], v227 offset:34816
	ds_read_b64 v[70:71], v215 offset:39456
	ds_read_b64 v[72:73], v227 offset:39456
	ds_read_b64 v[74:75], v215 offset:44096
	ds_read_b64 v[76:77], v227 offset:44096
	ds_read_b64 v[78:79], v215 offset:48736
	ds_read_b64 v[80:81], v227 offset:48736
	s_cbranch_vccz .LdiffA_noresc
	v_pk_mul_f32 v[50:51], v[50:51], v[244:245] op_sel_hi:[1,0]
	v_pk_mul_f32 v[52:53], v[52:53], v[244:245] op_sel_hi:[1,0]
	v_pk_mul_f32 v[54:55], v[54:55], v[244:245] op_sel_hi:[1,0]
	v_pk_mul_f32 v[56:57], v[56:57], v[244:245] op_sel_hi:[1,0]
	v_pk_mul_f32 v[58:59], v[58:59], v[244:245] op_sel_hi:[1,0]
	v_pk_mul_f32 v[60:61], v[60:61], v[244:245] op_sel_hi:[1,0]
	v_pk_mul_f32 v[62:63], v[62:63], v[244:245] op_sel_hi:[1,0]
	v_pk_mul_f32 v[64:65], v[64:65], v[244:245] op_sel_hi:[1,0]
	v_pk_mul_f32 v[34:35], v[34:35], v[244:245] op_sel_hi:[1,0]
	v_pk_mul_f32 v[36:37], v[36:37], v[244:245] op_sel_hi:[1,0]
	v_pk_mul_f32 v[38:39], v[38:39], v[244:245] op_sel_hi:[1,0]
	v_pk_mul_f32 v[40:41], v[40:41], v[244:245] op_sel_hi:[1,0]
	v_pk_mul_f32 v[42:43], v[42:43], v[244:245] op_sel_hi:[1,0]
	v_pk_mul_f32 v[44:45], v[44:45], v[244:245] op_sel_hi:[1,0]
	v_pk_mul_f32 v[46:47], v[46:47], v[244:245] op_sel_hi:[1,0]
	v_pk_mul_f32 v[48:49], v[48:49], v[244:245] op_sel_hi:[1,0]
	v_pk_mul_f32 v[18:19], v[18:19], v[244:245] op_sel_hi:[1,0]
	v_pk_mul_f32 v[20:21], v[20:21], v[244:245] op_sel_hi:[1,0]
	v_pk_mul_f32 v[22:23], v[22:23], v[244:245] op_sel_hi:[1,0]
	v_pk_mul_f32 v[24:25], v[24:25], v[244:245] op_sel_hi:[1,0]
	v_pk_mul_f32 v[26:27], v[26:27], v[244:245] op_sel_hi:[1,0]
	v_pk_mul_f32 v[28:29], v[28:29], v[244:245] op_sel_hi:[1,0]
	v_pk_mul_f32 v[30:31], v[30:31], v[244:245] op_sel_hi:[1,0]
	v_pk_mul_f32 v[32:33], v[32:33], v[244:245] op_sel_hi:[1,0]
	v_pk_mul_f32 v[2:3], v[2:3], v[244:245] op_sel_hi:[1,0]
	v_pk_mul_f32 v[4:5], v[4:5], v[244:245] op_sel_hi:[1,0]
	v_pk_mul_f32 v[6:7], v[6:7], v[244:245] op_sel_hi:[1,0]
	v_pk_mul_f32 v[8:9], v[8:9], v[244:245] op_sel_hi:[1,0]
	v_pk_mul_f32 v[10:11], v[10:11], v[244:245] op_sel_hi:[1,0]
	v_pk_mul_f32 v[12:13], v[12:13], v[244:245] op_sel_hi:[1,0]
	v_pk_mul_f32 v[14:15], v[14:15], v[244:245] op_sel_hi:[1,0]
	v_pk_mul_f32 v[16:17], v[16:17], v[244:245] op_sel_hi:[1,0]
; #define LAS __attribute__((address_space(3)))
; __device__ __forceinline__ f32x16 mma32(const h16x8 a, const h16x8 b, const f32x16 c) { return __builtin_amdgcn_mfma_f32_32x32x16_f16(a, b, c, 0, 0, 0); }
; __device__ __forceinline__ void diff_attn_item(CParams& p, int j, int layer, LAS unsigned char* lds, int b, int h, int qb, int tid_in, int lane_in, int wave) {
;     ...
; #pragma unroll
;         for (int sub = 0; sub < 2; ++sub)
; #pragma unroll
;             for (int s2 = 0; s2 < 2; ++s2) {
;                 h16x8 pf;
; #pragma unroll
;                 for (int jj = 0; jj < 8; ++jj) pf[jj] = (h16)sc[sub][8 * s2 + jj];
; #pragma unroll
;                 for (int d = 0; d < 4; ++d) {
;                     const int coff = 32 * d * 72 + ((((sub << 1) | s2) ^ d) << 4);
;                     const h16x4 lo = *(const LAS h16x4*)(Vt + vlo + coff), hi = *(const LAS h16x4*)(Vt + vhi + coff);
;                     h16x8 vf; vf[0] = lo[0]; vf[1] = lo[1]; vf[2] = lo[2]; vf[3] = lo[3]; vf[4] = hi[0]; vf[5] = hi[1]; vf[6] = hi[2]; vf[7] = hi[3];
;                     o[d] = mma32(vf, pf, o[d]);
;                 }
;             }
.LdiffA_noresc:
	ds_read_b64 v[82:83], v215 offset:34848
	ds_read_b64 v[84:85], v227 offset:34848
	ds_read_b64 v[86:87], v215 offset:39424
	ds_read_b64 v[88:89], v227 offset:39424
	ds_read_b64 v[90:91], v215 offset:44128
	ds_read_b64 v[92:93], v227 offset:44128
	ds_read_b64 v[94:95], v215 offset:48704
	ds_read_b64 v[96:97], v227 offset:48704
	s_waitcnt lgkmcnt(8)
	v_mfma_f32_32x32x16_f16 v[50:65], v[66:69], v[144:147], v[50:65]
	v_mfma_f32_32x32x16_f16 v[34:49], v[70:73], v[144:147], v[34:49]
	v_mfma_f32_32x32x16_f16 v[18:33], v[74:77], v[144:147], v[18:33]
	v_mfma_f32_32x32x16_f16 v[2:17], v[78:81], v[144:147], v[2:17]
	ds_read_b64 v[66:67], v215 offset:34880
	ds_read_b64 v[68:69], v227 offset:34880
	ds_read_b64 v[70:71], v215 offset:39520
	ds_read_b64 v[72:73], v227 offset:39520
	ds_read_b64 v[74:75], v215 offset:44032
	ds_read_b64 v[76:77], v227 offset:44032
	ds_read_b64 v[78:79], v215 offset:48672
	ds_read_b64 v[80:81], v227 offset:48672
	s_waitcnt lgkmcnt(8)
	v_mfma_f32_32x32x16_f16 v[50:65], v[82:85], v[148:151], v[50:65]
	v_mfma_f32_32x32x16_f16 v[34:49], v[86:89], v[148:151], v[34:49]
	v_mfma_f32_32x32x16_f16 v[18:33], v[90:93], v[148:151], v[18:33]
	v_mfma_f32_32x32x16_f16 v[2:17], v[94:97], v[148:151], v[2:17]
	ds_read_b64 v[82:83], v215 offset:34912
	ds_read_b64 v[84:85], v227 offset:34912
	ds_read_b64 v[86:87], v215 offset:39488
	ds_read_b64 v[88:89], v227 offset:39488
	ds_read_b64 v[90:91], v215 offset:44064
	ds_read_b64 v[92:93], v227 offset:44064
	ds_read_b64 v[94:95], v215 offset:48640
	ds_read_b64 v[96:97], v227 offset:48640
	s_waitcnt lgkmcnt(8)
	v_mfma_f32_32x32x16_f16 v[50:65], v[66:69], v[152:155], v[50:65]
	v_mfma_f32_32x32x16_f16 v[34:49], v[70:73], v[152:155], v[34:49]
	v_mfma_f32_32x32x16_f16 v[18:33], v[74:77], v[152:155], v[18:33]
	v_mfma_f32_32x32x16_f16 v[2:17], v[78:81], v[152:155], v[2:17]
	s_waitcnt lgkmcnt(0)
	v_mfma_f32_32x32x16_f16 v[50:65], v[82:85], v[178:181], v[50:65]
	v_mfma_f32_32x32x16_f16 v[34:49], v[86:89], v[178:181], v[34:49]
	v_mfma_f32_32x32x16_f16 v[18:33], v[90:93], v[178:181], v[18:33]
	v_mfma_f32_32x32x16_f16 v[2:17], v[94:97], v[178:181], v[2:17]
